# v141 + SSD conv: conv weights and bias staged once per phase in LDS (f32, same values), the 30 per-iteration weight/bias global loads become ds_read_b128
# speedup vs baseline: 1.0023x; 1.0023x over previous
.LBB0_151:
	s_and_b64 vcc, exec, s[4:5]
	s_cbranch_vccz .LBB0_314
	s_cmp_gt_i32 s0, 0
	s_mov_b64 s[4:5], -1
	s_cbranch_scc0 .LBB0_312
	s_cmp_gt_i32 s0, 1
	s_cbranch_scc0 .LBB0_254
	s_lshr_b32 s3, s64, 6
	s_mul_i32 s3, s3, 48
	s_cmp_ge_i32 s2, s3
	s_cbranch_scc1 .LBB0_253
	s_waitcnt vmcnt(0)
	v_ashrrev_i32_e32 v54, 3, v160
	s_movk_i32 s4, 0x8c
	v_and_b32_e32 v4, 7, v218
	v_mul_lo_u32 v0, v54, s4
	s_load_dwordx4 s[8:11], s[82:83], 0x60
	s_load_dwordx2 s[16:17], s[82:83], 0x18
	v_add_u32_e32 v5, 0, v0
	v_lshlrev_b32_e32 v0, 4, v4
	s_add_u32 s6, s54, 0x10380000
	v_lshl_add_u64 v[2:3], s[54:55], 0, v[0:1]
	s_mov_b64 s[4:5], 0x1cbc0000
	s_addc_u32 s7, s55, 0
	v_lshl_add_u64 v[58:59], v[2:3], 0, s[4:5]
	s_mov_b64 s[4:5], 0x171c0000
	s_add_u32 s14, s54, 0x1ddc0000
	v_ashrrev_i32_e32 v55, 31, v54
	v_lshl_add_u64 v[60:61], v[2:3], 0, s[4:5]
	v_mul_u32_u24_e32 v2, 0x460, v4
	v_lshlrev_b32_e32 v3, 1, v54
	s_addc_u32 s15, s55, 0
	s_add_i32 s42, s3, -1
	v_lshlrev_b32_e32 v56, 3, v4
	v_add_u32_e32 v57, -3, v54
	v_add3_u32 v120, 0, v2, v3
	v_lshlrev_b64 v[62:63], 7, v[54:55]
	s_lshl_b32 s43, s76, 1
	v_add_u32_e32 v121, v5, v0
	s_mov_b32 s46, s2
	s_waitcnt lgkmcnt(0)
	v_lshlrev_b32_e32 v228, 4, v160
	v_add_u32_e32 v230, 0x8000, v228
	global_load_dwordx4 v[142:145], v228, s[8:9]
	v_add_u32_e32 v229, 0x2000, v228
	global_load_dwordx4 v[146:149], v229, s[8:9]
	v_add_u32_e32 v229, 0x4000, v228
	global_load_dwordx4 v[150:153], v229, s[8:9]
	v_add_u32_e32 v229, 0x6000, v228
	global_load_dwordx4 v[162:165], v229, s[8:9]
	v_add_u32_e32 v229, 0x8000, v228
	global_load_dwordx4 v[166:169], v229, s[8:9]
	v_add_u32_e32 v229, 0xa000, v228
	global_load_dwordx4 v[170:173], v229, s[8:9]
	global_load_dwordx4 v[174:177], v228, s[10:11]
	v_cmp_gt_u32_e32 vcc, 0x100, v160
	s_and_saveexec_b64 s[98:99], vcc
	v_add_u32_e32 v229, 0x2000, v228
	global_load_dwordx4 v[178:181], v229, s[10:11]
	s_waitcnt vmcnt(0)
	ds_write_b128 v230, v[178:181] offset:57344
	s_mov_b64 exec, s[98:99]
	ds_write_b128 v230, v[142:145]
	ds_write_b128 v230, v[146:149] offset:8192
	ds_write_b128 v230, v[150:153] offset:16384
	ds_write_b128 v230, v[162:165] offset:24576
	ds_write_b128 v230, v[166:169] offset:32768
	ds_write_b128 v230, v[170:173] offset:40960
	ds_write_b128 v230, v[174:177] offset:49152
	s_waitcnt lgkmcnt(0)
	s_barrier
	s_branch .LBB0_158

.LBB0_224:
	s_or_b64 exec, exec, s[4:5]
	v_lshlrev_b64 v[52:53], 2, v[52:53]
	v_add_u32_e32 v233, 0x8000, v52
	v_lshl_add_u64 v[118:119], s[10:11], 0, v[52:53]
	v_lshl_add_u64 v[52:53], s[8:9], 0, v[52:53]
	v_add_co_u32_e32 v134, vcc, s86, v52
	ds_read_b128 v[114:117], v233 offset:49168
	ds_read_b128 v[122:125], v233 offset:49152
	ds_read_b128 v[126:129], v233 offset:16
	ds_read_b128 v[130:133], v233
	s_mov_b64 s[38:39], 0x3000
	v_addc_co_u32_e32 v135, vcc, 0, v53, vcc
	v_lshl_add_u64 v[118:119], v[52:53], 0, s[38:39]
	ds_read_b128 v[134:137], v233 offset:12288
	s_nop 0
	ds_read_b128 v[138:141], v233 offset:12304
	s_movk_i32 s4, 0x6000
	s_mov_b64 s[40:41], 0x6000
	s_mov_b64 s[48:49], 0x9000
	s_mov_b32 s5, 0x9000
	s_cmp_lt_i32 s20, 40
	s_waitcnt lgkmcnt(2)
	v_mov_b32_e32 v118, v130
	s_waitcnt lgkmcnt(1)
	v_mov_b32_e32 v119, v134
	v_pk_mul_f32 v[38:39], v[118:119], v[38:39]
	v_mov_b32_e32 v134, v131
	v_add_f32_e32 v0, v122, v38
	v_add_f32_e32 v0, v0, v39
	s_waitcnt lgkmcnt(0)
	v_mov_b32_e32 v38, v138
	v_mov_b32_e32 v39, v126
	v_mov_b32_e32 v126, v139
	v_pk_mul_f32 v[38:39], v[38:39], v[102:103]
	v_pk_mul_f32 v[10:11], v[126:127], v[10:11]
	v_add_f32_e32 v39, v39, v114
	v_add_f32_e32 v11, v11, v115
	v_add_f32_e32 v118, v38, v39
	v_pk_mul_f32 v[38:39], v[134:135], v[106:107]
	v_add_f32_e32 v107, v10, v11
	v_mov_b32_e32 v10, v132
	v_mov_b32_e32 v11, v136
	v_pk_mul_f32 v[10:11], v[10:11], v[40:41]
	v_mov_b32_e32 v136, v133
	v_add_f32_e32 v10, v124, v10
	v_add_f32_e32 v119, v10, v11
	v_mov_b32_e32 v10, v140
	v_mov_b32_e32 v11, v128
	v_pk_mul_f32 v[10:11], v[10:11], v[98:99]
	v_mov_b32_e32 v128, v141
	v_add_f32_e32 v11, v11, v116
	v_add_f32_e32 v122, v10, v11
	v_pk_mul_f32 v[10:11], v[136:137], v[100:101]
	v_add_f32_e32 v38, v123, v38
	v_add_f32_e32 v10, v125, v10
	v_add_f32_e32 v123, v10, v11
	v_pk_mul_f32 v[10:11], v[128:129], v[12:13]
	v_add_f32_e32 v106, v38, v39
	v_add_f32_e32 v11, v11, v117
	v_add_f32_e32 v124, v10, v11
	v_add_co_u32_e32 v10, vcc, s4, v52
	v_lshl_add_u64 v[38:39], v[52:53], 0, s[40:41]
	s_nop 0
	v_addc_co_u32_e32 v11, vcc, 0, v53, vcc
	v_lshl_add_u64 v[102:103], v[52:53], 0, s[48:49]
	v_add_co_u32_e32 v52, vcc, s5, v52
	ds_read_b128 v[10:13], v233 offset:24576
	s_nop 0
	ds_read_b128 v[38:41], v233 offset:24592
	v_addc_co_u32_e32 v53, vcc, 0, v53, vcc
	ds_read_b128 v[98:101], v233 offset:36864
	ds_read_b128 v[114:117], v233 offset:36880
	s_waitcnt lgkmcnt(3)
	v_mov_b32_e32 v52, v10
	s_waitcnt lgkmcnt(1)
	v_mov_b32_e32 v53, v98
	v_pk_mul_f32 v[46:47], v[52:53], v[46:47]
	v_mov_b32_e32 v98, v11
	v_add_f32_e32 v0, v0, v46
	v_add_f32_e32 v0, v0, v47
	s_waitcnt lgkmcnt(0)
	v_mov_b32_e32 v46, v114
	v_mov_b32_e32 v47, v38
	v_pk_mul_f32 v[46:47], v[46:47], v[110:111]
	v_mov_b32_e32 v38, v115
	v_add_f32_e32 v10, v47, v118
	v_add_f32_e32 v46, v46, v10
	v_pk_mul_f32 v[10:11], v[98:99], v[112:113]
	s_nop 0
	v_add_f32_e32 v10, v106, v10
	v_add_f32_e32 v47, v10, v11
	v_pk_mul_f32 v[10:11], v[38:39], v[42:43]
	s_nop 0
	v_add_f32_e32 v11, v11, v107
	v_add_f32_e32 v38, v10, v11
	v_mov_b32_e32 v10, v12
	v_mov_b32_e32 v11, v100
	v_pk_mul_f32 v[10:11], v[10:11], v[48:49]
	v_mov_b32_e32 v100, v13
	v_add_f32_e32 v10, v119, v10
	v_add_f32_e32 v12, v10, v11
	v_mov_b32_e32 v10, v116
	v_mov_b32_e32 v11, v40
	v_pk_mul_f32 v[10:11], v[10:11], v[104:105]
	v_mov_b32_e32 v40, v117
	v_add_f32_e32 v11, v11, v122
	v_add_f32_e32 v39, v10, v11
	v_pk_mul_f32 v[10:11], v[100:101], v[108:109]
	s_nop 0
	v_add_f32_e32 v10, v123, v10
	v_add_f32_e32 v13, v10, v11
	v_pk_mul_f32 v[10:11], v[40:41], v[44:45]
	v_mul_f32_e32 v40, 0xbfb8aa3b, v12
	v_exp_f32_e32 v40, v40
	v_mul_f32_e32 v41, 0xbfb8aa3b, v38
	v_exp_f32_e32 v41, v41
	v_add_f32_e32 v11, v11, v124
	v_add_f32_e32 v40, 1.0, v40
	v_rcp_f32_e32 v40, v40
	v_add_f32_e32 v41, 1.0, v41
	v_rcp_f32_e32 v41, v41
	v_add_f32_e32 v10, v10, v11
	v_mul_f32_e32 v11, 0xbfb8aa3b, v0
	v_mul_f32_e32 v12, v12, v40
	v_mul_f32_e32 v40, 0xbfb8aa3b, v13
	v_exp_f32_e32 v11, v11
	v_exp_f32_e32 v40, v40
	v_mul_f32_e32 v38, v38, v41
	v_mul_f32_e32 v41, 0xbfb8aa3b, v39
	v_exp_f32_e32 v41, v41
	v_add_f32_e32 v11, 1.0, v11
	v_add_f32_e32 v40, 1.0, v40
	v_rcp_f32_e32 v11, v11
	v_rcp_f32_e32 v40, v40
	v_add_f32_e32 v41, 1.0, v41
	v_rcp_f32_e32 v41, v41
	v_mul_f32_e32 v0, v0, v11
	v_mul_f32_e32 v11, 0xbfb8aa3b, v47
	v_mul_f32_e32 v13, v13, v40
	v_mul_f32_e32 v40, 0xbfb8aa3b, v46
	v_exp_f32_e32 v11, v11
	v_exp_f32_e32 v40, v40
	v_mul_f32_e32 v39, v39, v41
	v_mul_f32_e32 v41, 0xbfb8aa3b, v10
	v_exp_f32_e32 v41, v41
	v_add_f32_e32 v11, 1.0, v11
	v_add_f32_e32 v40, 1.0, v40
	v_rcp_f32_e32 v11, v11
	v_rcp_f32_e32 v40, v40
	v_add_f32_e32 v41, 1.0, v41
	v_rcp_f32_e32 v41, v41
	v_mul_f32_e32 v11, v47, v11
	v_mul_f32_e32 v40, v46, v40
	v_lshlrev_b64 v[46:47], 2, v[50:51]
	v_add_u32_e32 v233, 0x8000, v46
	v_lshl_add_u64 v[98:99], s[8:9], 0, v[46:47]
	v_mul_f32_e32 v41, v10, v41
	v_lshl_add_u64 v[42:43], s[10:11], 0, v[46:47]
	v_add_co_u32_e32 v102, vcc, s86, v98
	v_cvt_pk_bf16_f32 v10, v0, v11
	v_cvt_pk_bf16_f32 v11, v12, v13
	v_cvt_pk_bf16_f32 v12, v40, v38
	v_cvt_pk_bf16_f32 v13, v39, v41
	ds_read_b128 v[38:41], v233 offset:49168
	s_nop 0
	ds_read_b128 v[42:45], v233 offset:49152
	s_nop 0
	ds_read_b128 v[46:49], v233 offset:16
	ds_read_b128 v[50:53], v233
	v_addc_co_u32_e32 v103, vcc, 0, v99, vcc
	v_lshl_add_u64 v[100:101], v[98:99], 0, s[38:39]
	ds_read_b128 v[102:105], v233 offset:12288
	s_nop 0
	ds_read_b128 v[106:109], v233 offset:12304
	s_waitcnt lgkmcnt(2)
	v_mov_b32_e32 v100, v50
	s_waitcnt lgkmcnt(1)
	v_mov_b32_e32 v101, v102
	v_pk_mul_f32 v[34:35], v[100:101], v[34:35]
	v_mov_b32_e32 v102, v51
	v_add_f32_e32 v0, v42, v34
	v_add_f32_e32 v100, v0, v35
	s_waitcnt lgkmcnt(0)
	v_mov_b32_e32 v34, v106
	v_mov_b32_e32 v35, v46
	v_pk_mul_f32 v[34:35], v[34:35], v[94:95]
	v_mov_b32_e32 v46, v107
	v_add_f32_e32 v0, v35, v38
	v_add_f32_e32 v94, v34, v0
	v_pk_mul_f32 v[34:35], v[102:103], v[96:97]
	v_pk_mul_f32 v[30:31], v[46:47], v[30:31]
	v_add_f32_e32 v0, v43, v34
	v_add_f32_e32 v51, v0, v35
	v_add_f32_e32 v0, v31, v39
	v_add_f32_e32 v50, v30, v0
	v_mov_b32_e32 v30, v52
	v_mov_b32_e32 v31, v104
	v_pk_mul_f32 v[30:31], v[30:31], v[36:37]
	v_mov_b32_e32 v104, v53
	v_add_f32_e32 v0, v44, v30
	v_add_f32_e32 v0, v0, v31
	v_mov_b32_e32 v30, v108
	v_mov_b32_e32 v31, v48
	v_pk_mul_f32 v[30:31], v[30:31], v[90:91]
	v_mov_b32_e32 v48, v109
	v_add_f32_e32 v31, v31, v40
	v_add_f32_e32 v46, v30, v31
	v_pk_mul_f32 v[30:31], v[104:105], v[92:93]
	v_lshl_add_u64 v[42:43], v[98:99], 0, s[48:49]
	v_add_f32_e32 v30, v45, v30
	v_add_f32_e32 v47, v30, v31
	v_pk_mul_f32 v[30:31], v[48:49], v[32:33]
	v_add_co_u32_e32 v32, vcc, s4, v98
	v_add_f32_e32 v31, v31, v41
	s_nop 0
	v_addc_co_u32_e32 v33, vcc, 0, v99, vcc
	v_add_co_u32_e32 v38, vcc, s5, v98
	v_add_f32_e32 v48, v30, v31
	v_lshl_add_u64 v[30:31], v[98:99], 0, s[40:41]
	v_addc_co_u32_e32 v39, vcc, 0, v99, vcc
	ds_read_b128 v[34:37], v233 offset:24576
	s_nop 0
	ds_read_b128 v[30:33], v233 offset:24592
	s_nop 0
	ds_read_b128 v[38:41], v233 offset:36864
	s_nop 0
	ds_read_b128 v[42:45], v233 offset:36880
	s_waitcnt lgkmcnt(3)
	v_mov_b32_e32 v52, v34
	s_waitcnt lgkmcnt(1)
	v_mov_b32_e32 v53, v38
	v_pk_mul_f32 v[26:27], v[52:53], v[26:27]
	v_mov_b32_e32 v38, v35
	v_add_f32_e32 v26, v100, v26
	v_add_f32_e32 v34, v26, v27
	s_waitcnt lgkmcnt(0)
	v_mov_b32_e32 v26, v42
	v_mov_b32_e32 v27, v30
	v_pk_mul_f32 v[26:27], v[26:27], v[88:89]
	v_mov_b32_e32 v30, v43
	v_add_f32_e32 v27, v27, v94
	v_add_f32_e32 v42, v26, v27
	v_pk_mul_f32 v[26:27], v[38:39], v[86:87]
	v_pk_mul_f32 v[22:23], v[30:31], v[22:23]
	v_add_f32_e32 v26, v51, v26
	v_add_f32_e32 v23, v23, v50
	v_add_f32_e32 v26, v26, v27
	v_add_f32_e32 v27, v22, v23
	v_mov_b32_e32 v22, v36
	v_mov_b32_e32 v23, v40
	v_pk_mul_f32 v[22:23], v[22:23], v[28:29]
	v_mov_b32_e32 v40, v37
	v_add_f32_e32 v0, v0, v22
	v_add_f32_e32 v0, v0, v23
	v_mov_b32_e32 v22, v44
	v_mov_b32_e32 v23, v32
	v_pk_mul_f32 v[22:23], v[22:23], v[82:83]
	v_mov_b32_e32 v32, v45
	v_add_f32_e32 v23, v23, v46
	v_add_f32_e32 v28, v22, v23
	v_pk_mul_f32 v[22:23], v[40:41], v[84:85]
	s_nop 0
	v_add_f32_e32 v22, v47, v22
	v_add_f32_e32 v29, v22, v23
	v_pk_mul_f32 v[22:23], v[32:33], v[24:25]
	v_mul_f32_e32 v25, 0xbfb8aa3b, v0
	v_exp_f32_e32 v25, v25
	v_mul_f32_e32 v24, 0xbfb8aa3b, v26
	v_exp_f32_e32 v24, v24
	v_add_f32_e32 v23, v23, v48
	v_add_f32_e32 v25, 1.0, v25
	v_rcp_f32_e32 v25, v25
	v_add_f32_e32 v24, 1.0, v24
	v_rcp_f32_e32 v24, v24
	v_add_f32_e32 v22, v22, v23
	v_mul_f32_e32 v0, v0, v25
	v_mul_f32_e32 v25, 0xbfb8aa3b, v29
	v_exp_f32_e32 v25, v25
	v_mul_f32_e32 v24, v26, v24
	v_mul_f32_e32 v26, 0xbfb8aa3b, v42
	v_mul_f32_e32 v23, 0xbfb8aa3b, v34
	v_add_f32_e32 v25, 1.0, v25
	v_rcp_f32_e32 v25, v25
	v_exp_f32_e32 v26, v26
	v_exp_f32_e32 v23, v23
	v_mul_f32_e32 v25, v29, v25
	v_mul_f32_e32 v29, 0xbfb8aa3b, v27
	v_exp_f32_e32 v29, v29
	v_add_f32_e32 v26, 1.0, v26
	v_add_f32_e32 v23, 1.0, v23
	v_rcp_f32_e32 v26, v26
	v_add_f32_e32 v29, 1.0, v29
	v_rcp_f32_e32 v29, v29
	v_rcp_f32_e32 v23, v23
	v_mul_f32_e32 v26, v42, v26
	v_mul_f32_e32 v27, v27, v29
	v_mul_f32_e32 v29, 0xbfb8aa3b, v28
	v_exp_f32_e32 v29, v29
	v_mul_f32_e32 v23, v34, v23
	v_add_f32_e32 v29, 1.0, v29
	v_rcp_f32_e32 v29, v29
	s_nop 0
	v_mul_f32_e32 v28, v28, v29
	v_mul_f32_e32 v29, 0xbfb8aa3b, v22
	v_exp_f32_e32 v29, v29
	s_nop 0
	v_add_f32_e32 v29, 1.0, v29
	v_rcp_f32_e32 v29, v29
	s_nop 0
	v_mul_f32_e32 v29, v22, v29
	v_cvt_pk_bf16_f32 v22, v23, v24
	v_cvt_pk_bf16_f32 v24, v26, v27
	v_lshlrev_b64 v[26:27], 2, v[76:77]
	v_add_u32_e32 v233, 0x8000, v26
	v_lshl_add_u64 v[32:33], s[10:11], 0, v[26:27]
	v_lshl_add_u64 v[26:27], s[8:9], 0, v[26:27]
	v_add_co_u32_e32 v34, vcc, s86, v26
	v_cvt_pk_bf16_f32 v23, v0, v25
	v_cvt_pk_bf16_f32 v25, v28, v29
	ds_read_b128 v[28:31], v233 offset:49168
	ds_read_b128 v[40:43], v233 offset:49152
	ds_read_b128 v[44:47], v233 offset:16
	ds_read_b128 v[48:51], v233
	v_addc_co_u32_e32 v35, vcc, 0, v27, vcc
	v_lshl_add_u64 v[32:33], v[26:27], 0, s[38:39]
	ds_read_b128 v[82:85], v233 offset:12288
	ds_read_b128 v[86:89], v233 offset:12304
	s_waitcnt lgkmcnt(2)
	v_mov_b32_e32 v32, v48
	s_waitcnt lgkmcnt(1)
	v_mov_b32_e32 v33, v82
	v_pk_mul_f32 v[18:19], v[32:33], v[18:19]
	v_mov_b32_e32 v82, v49
	v_add_f32_e32 v0, v40, v18
	v_add_f32_e32 v40, v0, v19
	s_waitcnt lgkmcnt(0)
	v_mov_b32_e32 v18, v86
	v_mov_b32_e32 v19, v44
	v_pk_mul_f32 v[18:19], v[18:19], v[78:79]
	v_mov_b32_e32 v44, v87
	v_add_f32_e32 v0, v19, v28
	v_add_f32_e32 v39, v18, v0
	v_pk_mul_f32 v[18:19], v[82:83], v[80:81]
	v_pk_mul_f32 v[14:15], v[44:45], v[14:15]
	v_add_f32_e32 v0, v41, v18
	v_add_f32_e32 v38, v0, v19
	v_add_f32_e32 v0, v15, v29
	v_add_f32_e32 v37, v14, v0
	v_mov_b32_e32 v14, v50
	v_mov_b32_e32 v15, v84
	v_pk_mul_f32 v[14:15], v[14:15], v[20:21]
	v_mov_b32_e32 v84, v51
	v_add_f32_e32 v0, v42, v14
	v_add_f32_e32 v36, v0, v15
	v_mov_b32_e32 v14, v88
	v_mov_b32_e32 v15, v46
	v_pk_mul_f32 v[14:15], v[14:15], v[72:73]
	v_mov_b32_e32 v46, v89
	v_add_f32_e32 v0, v15, v30
	v_add_f32_e32 v35, v14, v0
	v_pk_mul_f32 v[14:15], v[84:85], v[74:75]
	s_nop 0
	v_add_f32_e32 v0, v43, v14
	v_add_f32_e32 v34, v0, v15
	v_pk_mul_f32 v[14:15], v[46:47], v[16:17]
	v_add_co_u32_e32 v16, vcc, s4, v26
	v_add_f32_e32 v0, v15, v31
	s_nop 0
	v_addc_co_u32_e32 v17, vcc, 0, v27, vcc
	v_add_f32_e32 v0, v14, v0
	v_lshl_add_u64 v[14:15], v[26:27], 0, s[40:41]
	v_lshl_add_u64 v[30:31], v[26:27], 0, s[48:49]
	v_add_co_u32_e32 v26, vcc, s5, v26
	ds_read_b128 v[18:21], v233 offset:24576
	s_nop 0
	ds_read_b128 v[14:17], v233 offset:24592
	v_addc_co_u32_e32 v27, vcc, 0, v27, vcc
	ds_read_b128 v[26:29], v233 offset:36864
	s_nop 0
	ds_read_b128 v[30:33], v233 offset:36880
	s_barrier
	s_waitcnt lgkmcnt(3)
	v_mov_b32_e32 v42, v18
	s_waitcnt lgkmcnt(1)
	v_mov_b32_e32 v43, v26
	v_pk_mul_f32 v[6:7], v[42:43], v[6:7]
	v_mov_b32_e32 v26, v19
	v_add_f32_e32 v6, v40, v6
	v_add_f32_e32 v18, v6, v7
	s_waitcnt lgkmcnt(0)
	v_mov_b32_e32 v6, v30
	v_mov_b32_e32 v7, v14
	v_pk_mul_f32 v[6:7], v[6:7], v[70:71]
	v_mov_b32_e32 v14, v31
	v_add_f32_e32 v7, v7, v39
	v_add_f32_e32 v30, v6, v7
	v_pk_mul_f32 v[6:7], v[26:27], v[68:69]
	v_pk_mul_f32 v[2:3], v[14:15], v[2:3]
	v_add_f32_e32 v6, v38, v6
	v_add_f32_e32 v3, v3, v37
	v_add_f32_e32 v6, v6, v7
	v_add_f32_e32 v7, v2, v3
	v_mov_b32_e32 v2, v20
	v_mov_b32_e32 v3, v28
	v_pk_mul_f32 v[2:3], v[2:3], v[8:9]
	v_mov_b32_e32 v28, v21
	v_add_f32_e32 v2, v36, v2
	v_add_f32_e32 v8, v2, v3
	v_mov_b32_e32 v2, v32
	v_mov_b32_e32 v3, v16
	v_pk_mul_f32 v[2:3], v[2:3], v[66:67]
	v_mov_b32_e32 v16, v33
	v_add_f32_e32 v3, v3, v35
	v_add_f32_e32 v9, v2, v3
	v_pk_mul_f32 v[2:3], v[28:29], v[64:65]
	s_nop 0
	v_add_f32_e32 v2, v34, v2
	v_add_f32_e32 v14, v2, v3
	v_pk_mul_f32 v[2:3], v[16:17], v[4:5]
	v_mul_f32_e32 v4, 0xbfb8aa3b, v8
	v_exp_f32_e32 v4, v4
	v_add_f32_e32 v0, v3, v0
	v_mul_f32_e32 v3, 0xbfb8aa3b, v6
	v_exp_f32_e32 v3, v3
	v_add_f32_e32 v4, 1.0, v4
	v_rcp_f32_e32 v4, v4
	v_add_f32_e32 v0, v2, v0
	v_add_f32_e32 v3, 1.0, v3
	v_rcp_f32_e32 v3, v3
	v_mul_f32_e32 v4, v8, v4
	v_mul_f32_e32 v8, 0xbfb8aa3b, v7
	v_exp_f32_e32 v8, v8
	v_mul_f32_e32 v2, 0xbfb8aa3b, v18
	v_mul_f32_e32 v3, v6, v3
	v_mul_f32_e32 v6, 0xbfb8aa3b, v30
	v_add_f32_e32 v8, 1.0, v8
	v_rcp_f32_e32 v8, v8
	v_exp_f32_e32 v2, v2
	v_mul_f32_e32 v5, 0xbfb8aa3b, v14
	v_exp_f32_e32 v6, v6
	v_mul_f32_e32 v7, v7, v8
	v_mul_f32_e32 v8, 0xbfb8aa3b, v9
	v_exp_f32_e32 v8, v8
	v_exp_f32_e32 v5, v5
	v_add_f32_e32 v2, 1.0, v2
	v_add_f32_e32 v6, 1.0, v6
	v_add_f32_e32 v8, 1.0, v8
	v_rcp_f32_e32 v8, v8
	v_rcp_f32_e32 v2, v2
	v_add_f32_e32 v5, 1.0, v5
	v_rcp_f32_e32 v6, v6
	v_mul_f32_e32 v8, v9, v8
	v_mul_f32_e32 v9, 0xbfb8aa3b, v0
	v_exp_f32_e32 v9, v9
	v_rcp_f32_e32 v5, v5
	v_mul_f32_e32 v2, v18, v2
	v_mul_f32_e32 v6, v30, v6
	v_add_f32_e32 v9, 1.0, v9
	v_rcp_f32_e32 v9, v9
	v_mul_f32_e32 v5, v14, v5
	v_cvt_pk_bf16_f32 v2, v2, v3
	v_cvt_pk_bf16_f32 v3, v4, v5
	v_mul_f32_e32 v0, v0, v9
	v_cvt_pk_bf16_f32 v4, v6, v7
	v_add_u32_e32 v6, s19, v54
	v_cvt_pk_bf16_f32 v5, v8, v0
	v_ashrrev_i32_e32 v7, 31, v6
	v_lshlrev_b32_e32 v0, 1, v56
	s_cbranch_scc1 .LBB0_226
	v_lshlrev_b64 v[8:9], 10, v[6:7]
	v_lshl_add_u64 v[8:9], s[14:15], 0, v[8:9]
	s_add_i32 s88, s22, 0xfffff600
	v_lshl_add_u64 v[8:9], s[88:89], 1, v[8:9]
	v_lshl_add_u64 v[8:9], v[8:9], 0, v[0:1]
	global_store_dwordx4 v[8:9], v[10:13], off
